# in-proj rotated K order with 16 distinct first slices (CU%16)
# baseline (speedup 1.0000x reference)
; template <int EPI>
; DI void gemm_phase(const P& p, int l, const u16* __restrict__ A, const u16* __restrict__ Bt, int mpx, char* lds) {
;     ...
;   while (true) {
;   const int tn = t + 1;
;   int m1 = 0, n1 = 0;
;   const bool has_next = tile_coords<EPI>(tn, mpx, m1, n1);
;   const u16* Agn = A + (size_t)m1 * 1024;
;   const u16* Bgn = Bt + (size_t)n1 * 1024;
;   f32x4 acc[8][4];
; #pragma unroll
;   for (int i = 0; i < 8; ++i)
; #pragma unroll
;     for (int j = 0; j < 4; ++j) acc[i][j] = zero4();
;   {
;   const int lane = tid & 63, w = tid >> 6, r = lane & 15, g = lane >> 4, wm = w >> 2, wn = w & 3;
;   __syncthreads();
;   GLOAD(Ag, Bg, 64)
.LBB0_81:
	s_mov_b32 s57, s3
	s_lshl_b64 s[42:43], s[56:57], 11
	s_lshl_b32 s2, s51, 11
	s_add_u32 s58, s16, s42
	s_addc_u32 s59, s17, s43
	s_add_u32 s60, s24, s2
	s_addc_u32 s61, s25, 0
	v_lshrrev_b32_e32 v166, 3, v195
	v_and_b32_e32 v167, 7, v195
	v_and_b32_e32 v168, 7, v166
	v_xor_b32_e32 v167, v167, v168
	v_lshlrev_b32_e32 v167, 4, v167
	v_lshl_or_b32 v162, v166, 11, v167
	v_add_u32_e32 v163, s33, v162
	v_add_u32_e32 v164, s35, v162
	v_add_u32_e32 v165, s39, v162
	v_readfirstlane_b32 s47, v195
	s_lshr_b32 s47, s47, 6
	s_lshl_b32 s47, s47, 10
	s_and_b32 s48, s84, 15
	s_lshl_b32 s48, s48, 0
	s_mov_b32 s49, 0
	s_waitcnt lgkmcnt(0)
	s_barrier
	s_cmp_eq_u32 s101, 0
	s_cbranch_scc1 .Lrot_in_nofirst
	s_mov_b32 s101, 0
	s_lshl_b32 s2, s48, 7
	s_add_u32 s44, s40, s2
	s_addc_u32 s45, s41, 0
	s_add_u32 s42, s0, s2
	s_addc_u32 s43, s1, 0
	s_add_i32 m0, s47, 0x20
	s_nop 0
	global_load_lds_dwordx4 v162, s[44:45]
	s_add_i32 m0, s47, 0x2020
	s_nop 0
	global_load_lds_dwordx4 v163, s[44:45]
	s_add_i32 m0, s47, 0x4020
	s_nop 0
	global_load_lds_dwordx4 v164, s[44:45]
	s_add_i32 m0, s47, 0x6020
	s_nop 0
	global_load_lds_dwordx4 v165, s[44:45]
	s_add_i32 m0, s47, 0x8020
	s_nop 0
	global_load_lds_dwordx4 v162, s[42:43]
	s_add_i32 m0, s47, 0xa020
	s_nop 0
	global_load_lds_dwordx4 v163, s[42:43]
	s_add_i32 m0, s47, 0xc020
	s_nop 0
	global_load_lds_dwordx4 v164, s[42:43]
	s_add_i32 m0, s47, 0xe020
	s_nop 0
	global_load_lds_dwordx4 v165, s[42:43]
	s_waitcnt vmcnt(0)
	s_barrier

; #define GCOMPUTE(AS, BS) GCOMPUTE_KS(AS, BS, 0) GCOMPUTE_KS(AS, BS, 1)
; template <int EPI>
; DI void gemm_phase(const P& p, int l, const u16* __restrict__ A, const u16* __restrict__ Bt, int mpx, char* lds) {
;     ...
;   for (int kk = 1; kk < 15; kk += 2) {
;     __syncthreads();
;     GSTORE(As0, Bs0)
;     GLOAD(Ag, Bg, (kk + 2) * 64)
;     __builtin_amdgcn_sched_barrier(0);
;     GCOMPUTE(As1, Bs1)
;     __builtin_amdgcn_sched_barrier(0);
.LBB0_82:
	s_waitcnt lgkmcnt(3)
	v_mfma_f32_16x16x32_bf16 v[6:9], v[238:241], v[212:215], v[6:9]
	v_mfma_f32_16x16x32_bf16 v[10:13], v[238:241], v[216:219], v[10:13]
	v_mfma_f32_16x16x32_bf16 v[14:17], v[238:241], v[220:223], v[14:17]
	v_mfma_f32_16x16x32_bf16 v[18:21], v[238:241], v[234:237], v[18:21]
	ds_read_b128 v[238:241], v199 offset:8192
	s_add_i32 m0, s47, 0x20
	s_nop 0
	global_load_lds_dwordx4 v162, s[44:45]
	s_add_i32 m0, s47, 0x2020
	s_nop 0
	global_load_lds_dwordx4 v163, s[44:45]
	s_waitcnt lgkmcnt(3)
	v_mfma_f32_16x16x32_bf16 v[22:25], v[242:245], v[212:215], v[22:25]
	v_mfma_f32_16x16x32_bf16 v[26:29], v[242:245], v[216:219], v[26:29]
	v_mfma_f32_16x16x32_bf16 v[30:33], v[242:245], v[220:223], v[30:33]
	v_mfma_f32_16x16x32_bf16 v[34:37], v[242:245], v[234:237], v[34:37]
	ds_read_b128 v[242:245], v199 offset:10240
	ds_read_b128 v[130:133], v200
	s_add_i32 m0, s47, 0x4020
	s_nop 0
	global_load_lds_dwordx4 v164, s[44:45]
	s_add_i32 m0, s47, 0x6020
	s_nop 0
	global_load_lds_dwordx4 v165, s[44:45]
	s_waitcnt lgkmcnt(4)
	v_mfma_f32_16x16x32_bf16 v[38:41], v[246:249], v[212:215], v[38:41]
	v_mfma_f32_16x16x32_bf16 v[42:45], v[246:249], v[216:219], v[42:45]
	v_mfma_f32_16x16x32_bf16 v[46:49], v[246:249], v[220:223], v[46:49]
	v_mfma_f32_16x16x32_bf16 v[50:53], v[246:249], v[234:237], v[50:53]
	ds_read_b128 v[246:249], v199 offset:12288
	ds_read_b128 v[134:137], v200 offset:2048
	s_add_i32 m0, s47, 0x8020
	s_nop 0
	global_load_lds_dwordx4 v162, s[42:43]
	s_add_i32 m0, s47, 0xa020
	s_nop 0
	global_load_lds_dwordx4 v163, s[42:43]
	s_waitcnt lgkmcnt(5)
	v_mfma_f32_16x16x32_bf16 v[54:57], v[250:253], v[212:215], v[54:57]
	v_mfma_f32_16x16x32_bf16 v[58:61], v[250:253], v[216:219], v[58:61]
	v_mfma_f32_16x16x32_bf16 v[62:65], v[250:253], v[220:223], v[62:65]
	v_mfma_f32_16x16x32_bf16 v[66:69], v[250:253], v[234:237], v[66:69]
	ds_read_b128 v[250:253], v199 offset:14336
	ds_read_b128 v[138:141], v200 offset:4096
	s_add_i32 m0, s47, 0xc020
	s_nop 0
	global_load_lds_dwordx4 v164, s[42:43]
	s_add_i32 m0, s47, 0xe020
	s_nop 0
	global_load_lds_dwordx4 v165, s[42:43]
	s_waitcnt lgkmcnt(6)
	v_mfma_f32_16x16x32_bf16 v[70:73], v[238:241], v[212:215], v[70:73]
	v_mfma_f32_16x16x32_bf16 v[74:77], v[238:241], v[216:219], v[74:77]
	v_mfma_f32_16x16x32_bf16 v[78:81], v[238:241], v[220:223], v[78:81]
	v_mfma_f32_16x16x32_bf16 v[82:85], v[238:241], v[234:237], v[82:85]
	ds_read_b128 v[238:241], v233
	ds_read_b128 v[142:145], v200 offset:6144
	s_waitcnt lgkmcnt(7)
	v_mfma_f32_16x16x32_bf16 v[86:89], v[242:245], v[212:215], v[86:89]
	v_mfma_f32_16x16x32_bf16 v[90:93], v[242:245], v[216:219], v[90:93]
	v_mfma_f32_16x16x32_bf16 v[94:97], v[242:245], v[220:223], v[94:97]
	v_mfma_f32_16x16x32_bf16 v[98:101], v[242:245], v[234:237], v[98:101]
	ds_read_b128 v[242:245], v233 offset:2048
	s_waitcnt lgkmcnt(6)
	v_mfma_f32_16x16x32_bf16 v[102:105], v[246:249], v[212:215], v[102:105]
	v_mfma_f32_16x16x32_bf16 v[106:109], v[246:249], v[216:219], v[106:109]
	v_mfma_f32_16x16x32_bf16 v[110:113], v[246:249], v[220:223], v[110:113]
	v_mfma_f32_16x16x32_bf16 v[114:117], v[246:249], v[234:237], v[114:117]
	ds_read_b128 v[246:249], v233 offset:4096
	s_waitcnt lgkmcnt(5)
	v_mfma_f32_16x16x32_bf16 v[118:121], v[250:253], v[212:215], v[118:121]
	v_mfma_f32_16x16x32_bf16 v[122:125], v[250:253], v[216:219], v[122:125]
	v_mfma_f32_16x16x32_bf16 v[126:129], v[250:253], v[220:223], v[126:129]
	v_mfma_f32_16x16x32_bf16 v[2:5], v[250:253], v[234:237], v[2:5]
	ds_read_b128 v[250:253], v233 offset:6144
	s_waitcnt lgkmcnt(3)
	v_mfma_f32_16x16x32_bf16 v[6:9], v[238:241], v[130:133], v[6:9]
	v_mfma_f32_16x16x32_bf16 v[10:13], v[238:241], v[134:137], v[10:13]
	v_mfma_f32_16x16x32_bf16 v[14:17], v[238:241], v[138:141], v[14:17]
	v_mfma_f32_16x16x32_bf16 v[18:21], v[238:241], v[142:145], v[18:21]
	ds_read_b128 v[238:241], v233 offset:8192
	s_waitcnt lgkmcnt(3)
	v_mfma_f32_16x16x32_bf16 v[22:25], v[242:245], v[130:133], v[22:25]
	v_mfma_f32_16x16x32_bf16 v[26:29], v[242:245], v[134:137], v[26:29]
	v_mfma_f32_16x16x32_bf16 v[30:33], v[242:245], v[138:141], v[30:33]
	v_mfma_f32_16x16x32_bf16 v[34:37], v[242:245], v[142:145], v[34:37]
	ds_read_b128 v[242:245], v233 offset:10240
	s_waitcnt lgkmcnt(3)
	v_mfma_f32_16x16x32_bf16 v[38:41], v[246:249], v[130:133], v[38:41]
	v_mfma_f32_16x16x32_bf16 v[42:45], v[246:249], v[134:137], v[42:45]
	v_mfma_f32_16x16x32_bf16 v[46:49], v[246:249], v[138:141], v[46:49]
	v_mfma_f32_16x16x32_bf16 v[50:53], v[246:249], v[142:145], v[50:53]
	ds_read_b128 v[246:249], v233 offset:12288
	s_waitcnt lgkmcnt(3)
	v_mfma_f32_16x16x32_bf16 v[54:57], v[250:253], v[130:133], v[54:57]
	v_mfma_f32_16x16x32_bf16 v[58:61], v[250:253], v[134:137], v[58:61]
	v_mfma_f32_16x16x32_bf16 v[62:65], v[250:253], v[138:141], v[62:65]
	v_mfma_f32_16x16x32_bf16 v[66:69], v[250:253], v[142:145], v[66:69]
	ds_read_b128 v[250:253], v233 offset:14336
	s_waitcnt lgkmcnt(3)
	v_mfma_f32_16x16x32_bf16 v[70:73], v[238:241], v[130:133], v[70:73]
	v_mfma_f32_16x16x32_bf16 v[74:77], v[238:241], v[134:137], v[74:77]
	v_mfma_f32_16x16x32_bf16 v[78:81], v[238:241], v[138:141], v[78:81]
	v_mfma_f32_16x16x32_bf16 v[82:85], v[238:241], v[142:145], v[82:85]
	s_waitcnt lgkmcnt(2)
	v_mfma_f32_16x16x32_bf16 v[86:89], v[242:245], v[130:133], v[86:89]
	v_mfma_f32_16x16x32_bf16 v[90:93], v[242:245], v[134:137], v[90:93]
	v_mfma_f32_16x16x32_bf16 v[94:97], v[242:245], v[138:141], v[94:97]
	v_mfma_f32_16x16x32_bf16 v[98:101], v[242:245], v[142:145], v[98:101]
	s_waitcnt lgkmcnt(0)
	s_waitcnt vmcnt(0)
	s_add_i32 s48, s48, 1
	s_and_b32 s48, s48, 15
	s_lshl_b32 s2, s48, 7
	s_add_u32 s44, s40, s2
	s_addc_u32 s45, s41, 0
	s_add_u32 s42, s0, s2
	s_addc_u32 s43, s1, 0
	s_barrier
; #define GCOMPUTE(AS, BS) GCOMPUTE_KS(AS, BS, 0) GCOMPUTE_KS(AS, BS, 1)
; template <int EPI>
; DI void gemm_phase(const P& p, int l, const u16* __restrict__ A, const u16* __restrict__ Bt, int mpx, char* lds) {
;     ...
;     __syncthreads();
;     GSTORE(As1, Bs1)
;     {
;       const bool in_tile = kk + 3 < 16;
;       const u16* pa = in_tile ? Ag : Agn;
;       const u16* pb = in_tile ? Bg : Bgn;
;       const int k0 = in_tile ? (kk + 3) * 64 : 0;
;       GLOAD(pa, pb, k0)
;     }
;     __builtin_amdgcn_sched_barrier(0);
;     GCOMPUTE(As0, Bs0)
;     __builtin_amdgcn_sched_barrier(0);
;   }
	ds_read_b128 v[212:215], v204 offset:32768
	ds_read_b128 v[216:219], v204 offset:34816
	ds_read_b128 v[220:223], v204 offset:36864
	ds_read_b128 v[234:237], v204 offset:38912
	ds_read_b128 v[238:241], v205
	ds_read_b128 v[242:245], v205 offset:2048
	v_mfma_f32_16x16x32_bf16 v[102:105], v[246:249], v[130:133], v[102:105]
	v_mfma_f32_16x16x32_bf16 v[106:109], v[246:249], v[134:137], v[106:109]
	v_mfma_f32_16x16x32_bf16 v[110:113], v[246:249], v[138:141], v[110:113]
	v_mfma_f32_16x16x32_bf16 v[114:117], v[246:249], v[142:145], v[114:117]
	ds_read_b128 v[246:249], v205 offset:4096
	v_mfma_f32_16x16x32_bf16 v[118:121], v[250:253], v[130:133], v[118:121]
	v_mfma_f32_16x16x32_bf16 v[122:125], v[250:253], v[134:137], v[122:125]
	v_mfma_f32_16x16x32_bf16 v[126:129], v[250:253], v[138:141], v[126:129]
	v_mfma_f32_16x16x32_bf16 v[2:5], v[250:253], v[142:145], v[2:5]
	ds_read_b128 v[250:253], v205 offset:6144
	s_waitcnt lgkmcnt(3)
	v_mfma_f32_16x16x32_bf16 v[6:9], v[238:241], v[212:215], v[6:9]
	v_mfma_f32_16x16x32_bf16 v[10:13], v[238:241], v[216:219], v[10:13]
	v_mfma_f32_16x16x32_bf16 v[14:17], v[238:241], v[220:223], v[14:17]
	v_mfma_f32_16x16x32_bf16 v[18:21], v[238:241], v[234:237], v[18:21]
	ds_read_b128 v[238:241], v205 offset:8192
	s_add_i32 m0, s47, 0x10020
	s_nop 0
	global_load_lds_dwordx4 v162, s[44:45]
	s_add_i32 m0, s47, 0x12020
	s_nop 0
	global_load_lds_dwordx4 v163, s[44:45]
	s_waitcnt lgkmcnt(3)
	v_mfma_f32_16x16x32_bf16 v[22:25], v[242:245], v[212:215], v[22:25]
	v_mfma_f32_16x16x32_bf16 v[26:29], v[242:245], v[216:219], v[26:29]
	v_mfma_f32_16x16x32_bf16 v[30:33], v[242:245], v[220:223], v[30:33]
	v_mfma_f32_16x16x32_bf16 v[34:37], v[242:245], v[234:237], v[34:37]
	ds_read_b128 v[242:245], v205 offset:10240
	ds_read_b128 v[130:133], v206 offset:32768
	s_add_i32 m0, s47, 0x14020
	s_nop 0
	global_load_lds_dwordx4 v164, s[44:45]
	s_add_i32 m0, s47, 0x16020
	s_nop 0
	global_load_lds_dwordx4 v165, s[44:45]
	s_waitcnt lgkmcnt(4)
	v_mfma_f32_16x16x32_bf16 v[38:41], v[246:249], v[212:215], v[38:41]
	v_mfma_f32_16x16x32_bf16 v[42:45], v[246:249], v[216:219], v[42:45]
	v_mfma_f32_16x16x32_bf16 v[46:49], v[246:249], v[220:223], v[46:49]
	v_mfma_f32_16x16x32_bf16 v[50:53], v[246:249], v[234:237], v[50:53]
	ds_read_b128 v[246:249], v205 offset:12288
	ds_read_b128 v[134:137], v206 offset:34816
	s_add_i32 m0, s47, 0x18020
	s_nop 0
	global_load_lds_dwordx4 v162, s[42:43]
	s_add_i32 m0, s47, 0x1a020
	s_nop 0
	global_load_lds_dwordx4 v163, s[42:43]
	s_waitcnt lgkmcnt(5)
	v_mfma_f32_16x16x32_bf16 v[54:57], v[250:253], v[212:215], v[54:57]
	v_mfma_f32_16x16x32_bf16 v[58:61], v[250:253], v[216:219], v[58:61]
	v_mfma_f32_16x16x32_bf16 v[62:65], v[250:253], v[220:223], v[62:65]
	v_mfma_f32_16x16x32_bf16 v[66:69], v[250:253], v[234:237], v[66:69]
	ds_read_b128 v[250:253], v205 offset:14336
	ds_read_b128 v[138:141], v206 offset:36864
	s_add_i32 m0, s47, 0x1c020
	s_nop 0
	global_load_lds_dwordx4 v164, s[42:43]
	s_add_i32 m0, s47, 0x1e020
	s_nop 0
	global_load_lds_dwordx4 v165, s[42:43]
	s_waitcnt lgkmcnt(6)
	v_mfma_f32_16x16x32_bf16 v[70:73], v[238:241], v[212:215], v[70:73]
	v_mfma_f32_16x16x32_bf16 v[74:77], v[238:241], v[216:219], v[74:77]
	v_mfma_f32_16x16x32_bf16 v[78:81], v[238:241], v[220:223], v[78:81]
	v_mfma_f32_16x16x32_bf16 v[82:85], v[238:241], v[234:237], v[82:85]
	ds_read_b128 v[238:241], v207
	ds_read_b128 v[142:145], v206 offset:38912
	s_waitcnt lgkmcnt(7)
	v_mfma_f32_16x16x32_bf16 v[86:89], v[242:245], v[212:215], v[86:89]
	v_mfma_f32_16x16x32_bf16 v[90:93], v[242:245], v[216:219], v[90:93]
	v_mfma_f32_16x16x32_bf16 v[94:97], v[242:245], v[220:223], v[94:97]
	v_mfma_f32_16x16x32_bf16 v[98:101], v[242:245], v[234:237], v[98:101]
	ds_read_b128 v[242:245], v207 offset:2048
	s_waitcnt lgkmcnt(6)
	v_mfma_f32_16x16x32_bf16 v[102:105], v[246:249], v[212:215], v[102:105]
	v_mfma_f32_16x16x32_bf16 v[106:109], v[246:249], v[216:219], v[106:109]
	v_mfma_f32_16x16x32_bf16 v[110:113], v[246:249], v[220:223], v[110:113]
	v_mfma_f32_16x16x32_bf16 v[114:117], v[246:249], v[234:237], v[114:117]
	ds_read_b128 v[246:249], v207 offset:4096
	s_waitcnt lgkmcnt(5)
	v_mfma_f32_16x16x32_bf16 v[118:121], v[250:253], v[212:215], v[118:121]
	v_mfma_f32_16x16x32_bf16 v[122:125], v[250:253], v[216:219], v[122:125]
	v_mfma_f32_16x16x32_bf16 v[126:129], v[250:253], v[220:223], v[126:129]
	v_mfma_f32_16x16x32_bf16 v[2:5], v[250:253], v[234:237], v[2:5]
	ds_read_b128 v[250:253], v207 offset:6144
	s_waitcnt lgkmcnt(3)
	v_mfma_f32_16x16x32_bf16 v[6:9], v[238:241], v[130:133], v[6:9]
	v_mfma_f32_16x16x32_bf16 v[10:13], v[238:241], v[134:137], v[10:13]
	v_mfma_f32_16x16x32_bf16 v[14:17], v[238:241], v[138:141], v[14:17]
	v_mfma_f32_16x16x32_bf16 v[18:21], v[238:241], v[142:145], v[18:21]
	ds_read_b128 v[238:241], v207 offset:8192
	s_waitcnt lgkmcnt(3)
	v_mfma_f32_16x16x32_bf16 v[22:25], v[242:245], v[130:133], v[22:25]
	v_mfma_f32_16x16x32_bf16 v[26:29], v[242:245], v[134:137], v[26:29]
	v_mfma_f32_16x16x32_bf16 v[30:33], v[242:245], v[138:141], v[30:33]
	v_mfma_f32_16x16x32_bf16 v[34:37], v[242:245], v[142:145], v[34:37]
	ds_read_b128 v[242:245], v207 offset:10240
	s_waitcnt lgkmcnt(3)
	v_mfma_f32_16x16x32_bf16 v[38:41], v[246:249], v[130:133], v[38:41]
	v_mfma_f32_16x16x32_bf16 v[42:45], v[246:249], v[134:137], v[42:45]
	v_mfma_f32_16x16x32_bf16 v[46:49], v[246:249], v[138:141], v[46:49]
	v_mfma_f32_16x16x32_bf16 v[50:53], v[246:249], v[142:145], v[50:53]
	ds_read_b128 v[246:249], v207 offset:12288
	s_waitcnt lgkmcnt(3)
	v_mfma_f32_16x16x32_bf16 v[54:57], v[250:253], v[130:133], v[54:57]
	v_mfma_f32_16x16x32_bf16 v[58:61], v[250:253], v[134:137], v[58:61]
	v_mfma_f32_16x16x32_bf16 v[62:65], v[250:253], v[138:141], v[62:65]
	v_mfma_f32_16x16x32_bf16 v[66:69], v[250:253], v[142:145], v[66:69]
	ds_read_b128 v[250:253], v207 offset:14336
	s_waitcnt lgkmcnt(3)
	v_mfma_f32_16x16x32_bf16 v[70:73], v[238:241], v[130:133], v[70:73]
	v_mfma_f32_16x16x32_bf16 v[74:77], v[238:241], v[134:137], v[74:77]
	v_mfma_f32_16x16x32_bf16 v[78:81], v[238:241], v[138:141], v[78:81]
	v_mfma_f32_16x16x32_bf16 v[82:85], v[238:241], v[142:145], v[82:85]
	s_waitcnt lgkmcnt(2)
	v_mfma_f32_16x16x32_bf16 v[86:89], v[242:245], v[130:133], v[86:89]
	v_mfma_f32_16x16x32_bf16 v[90:93], v[242:245], v[134:137], v[90:93]
	v_mfma_f32_16x16x32_bf16 v[94:97], v[242:245], v[138:141], v[94:97]
	v_mfma_f32_16x16x32_bf16 v[98:101], v[242:245], v[142:145], v[98:101]
	s_waitcnt lgkmcnt(0)
	s_waitcnt vmcnt(0)
	s_add_i32 s48, s48, 1
	s_and_b32 s48, s48, 15
	s_lshl_b32 s2, s48, 7
	s_add_u32 s44, s40, s2
	s_addc_u32 s45, s41, 0
	s_add_u32 s42, s0, s2
	s_addc_u32 s43, s1, 0
	s_add_i32 s49, s49, 1
	s_cmp_lt_u32 s49, 7
	s_barrier
; #define GCOMPUTE(AS, BS) GCOMPUTE_KS(AS, BS, 0) GCOMPUTE_KS(AS, BS, 1)
; template <int EPI>
; DI void gemm_phase(const P& p, int l, const u16* __restrict__ A, const u16* __restrict__ Bt, int mpx, char* lds) {
;     ...
;     __syncthreads();
;     GSTORE(As1, Bs1)
;     {
;       const bool in_tile = kk + 3 < 16;
;       const u16* pa = in_tile ? Ag : Agn;
;       const u16* pb = in_tile ? Bg : Bgn;
;       const int k0 = in_tile ? (kk + 3) * 64 : 0;
;       GLOAD(pa, pb, k0)
;     }
;     __builtin_amdgcn_sched_barrier(0);
;     GCOMPUTE(As0, Bs0)
;     __builtin_amdgcn_sched_barrier(0);
;   }
;   __syncthreads();
;   __builtin_amdgcn_sched_barrier(0);
;   GCOMPUTE(As1, Bs1)
;   __builtin_amdgcn_sched_barrier(0);
;   }
;   __syncthreads();
;   GSTORE(As0, Bs0)
	ds_read_b128 v[212:215], v198
	ds_read_b128 v[216:219], v198 offset:2048
	ds_read_b128 v[220:223], v198 offset:4096
	ds_read_b128 v[234:237], v198 offset:6144
	ds_read_b128 v[238:241], v199
	ds_read_b128 v[242:245], v199 offset:2048
	v_mfma_f32_16x16x32_bf16 v[102:105], v[246:249], v[130:133], v[102:105]
	v_mfma_f32_16x16x32_bf16 v[106:109], v[246:249], v[134:137], v[106:109]
	v_mfma_f32_16x16x32_bf16 v[110:113], v[246:249], v[138:141], v[110:113]
	v_mfma_f32_16x16x32_bf16 v[114:117], v[246:249], v[142:145], v[114:117]
	ds_read_b128 v[246:249], v199 offset:4096
	v_mfma_f32_16x16x32_bf16 v[118:121], v[250:253], v[130:133], v[118:121]
	v_mfma_f32_16x16x32_bf16 v[122:125], v[250:253], v[134:137], v[122:125]
	v_mfma_f32_16x16x32_bf16 v[126:129], v[250:253], v[138:141], v[126:129]
	v_mfma_f32_16x16x32_bf16 v[2:5], v[250:253], v[142:145], v[2:5]
	ds_read_b128 v[250:253], v199 offset:6144
	s_cbranch_scc1 .LBB0_82
	s_and_b32 s2, s84, 15
	s_lshl_b32 s2, s2, 7
	s_add_u32 s44, s58, s2
	s_addc_u32 s45, s59, 0
	s_add_u32 s42, s60, s2
	s_addc_u32 s43, s61, 0
	s_waitcnt lgkmcnt(3)
	v_mfma_f32_16x16x32_bf16 v[6:9], v[238:241], v[212:215], v[6:9]
	v_mfma_f32_16x16x32_bf16 v[10:13], v[238:241], v[216:219], v[10:13]
	v_mfma_f32_16x16x32_bf16 v[14:17], v[238:241], v[220:223], v[14:17]
	v_mfma_f32_16x16x32_bf16 v[18:21], v[238:241], v[234:237], v[18:21]
	ds_read_b128 v[238:241], v199 offset:8192
	s_add_i32 m0, s47, 0x20
	s_nop 0
	global_load_lds_dwordx4 v162, s[44:45]
	s_add_i32 m0, s47, 0x2020
	s_nop 0
	global_load_lds_dwordx4 v163, s[44:45]
	s_waitcnt lgkmcnt(3)
	v_mfma_f32_16x16x32_bf16 v[22:25], v[242:245], v[212:215], v[22:25]
	v_mfma_f32_16x16x32_bf16 v[26:29], v[242:245], v[216:219], v[26:29]
	v_mfma_f32_16x16x32_bf16 v[30:33], v[242:245], v[220:223], v[30:33]
	v_mfma_f32_16x16x32_bf16 v[34:37], v[242:245], v[234:237], v[34:37]
	ds_read_b128 v[242:245], v199 offset:10240
	ds_read_b128 v[130:133], v200
	s_add_i32 m0, s47, 0x4020
	s_nop 0
	global_load_lds_dwordx4 v164, s[44:45]
	s_add_i32 m0, s47, 0x6020
	s_nop 0
	global_load_lds_dwordx4 v165, s[44:45]
	s_waitcnt lgkmcnt(4)
	v_mfma_f32_16x16x32_bf16 v[38:41], v[246:249], v[212:215], v[38:41]
	v_mfma_f32_16x16x32_bf16 v[42:45], v[246:249], v[216:219], v[42:45]
	v_mfma_f32_16x16x32_bf16 v[46:49], v[246:249], v[220:223], v[46:49]
	v_mfma_f32_16x16x32_bf16 v[50:53], v[246:249], v[234:237], v[50:53]
	ds_read_b128 v[246:249], v199 offset:12288
	ds_read_b128 v[134:137], v200 offset:2048
	s_add_i32 m0, s47, 0x8020
	s_nop 0
	global_load_lds_dwordx4 v162, s[42:43]
	s_add_i32 m0, s47, 0xa020
	s_nop 0
	global_load_lds_dwordx4 v163, s[42:43]
	s_waitcnt lgkmcnt(5)
	v_mfma_f32_16x16x32_bf16 v[54:57], v[250:253], v[212:215], v[54:57]
	v_mfma_f32_16x16x32_bf16 v[58:61], v[250:253], v[216:219], v[58:61]
	v_mfma_f32_16x16x32_bf16 v[62:65], v[250:253], v[220:223], v[62:65]
	v_mfma_f32_16x16x32_bf16 v[66:69], v[250:253], v[234:237], v[66:69]
	ds_read_b128 v[250:253], v199 offset:14336
	ds_read_b128 v[138:141], v200 offset:4096
	s_add_i32 m0, s47, 0xc020
	s_nop 0
	global_load_lds_dwordx4 v164, s[42:43]
	s_add_i32 m0, s47, 0xe020
	s_nop 0
	global_load_lds_dwordx4 v165, s[42:43]
	s_waitcnt lgkmcnt(6)
	v_mfma_f32_16x16x32_bf16 v[70:73], v[238:241], v[212:215], v[70:73]
	v_mfma_f32_16x16x32_bf16 v[74:77], v[238:241], v[216:219], v[74:77]
	v_mfma_f32_16x16x32_bf16 v[78:81], v[238:241], v[220:223], v[78:81]
	v_mfma_f32_16x16x32_bf16 v[82:85], v[238:241], v[234:237], v[82:85]
	ds_read_b128 v[238:241], v233
	ds_read_b128 v[142:145], v200 offset:6144
	s_waitcnt lgkmcnt(7)
	v_mfma_f32_16x16x32_bf16 v[86:89], v[242:245], v[212:215], v[86:89]
	v_mfma_f32_16x16x32_bf16 v[90:93], v[242:245], v[216:219], v[90:93]
	v_mfma_f32_16x16x32_bf16 v[94:97], v[242:245], v[220:223], v[94:97]
	v_mfma_f32_16x16x32_bf16 v[98:101], v[242:245], v[234:237], v[98:101]
	ds_read_b128 v[242:245], v233 offset:2048
	s_waitcnt lgkmcnt(6)
	v_mfma_f32_16x16x32_bf16 v[102:105], v[246:249], v[212:215], v[102:105]
	v_mfma_f32_16x16x32_bf16 v[106:109], v[246:249], v[216:219], v[106:109]
	v_mfma_f32_16x16x32_bf16 v[110:113], v[246:249], v[220:223], v[110:113]
	v_mfma_f32_16x16x32_bf16 v[114:117], v[246:249], v[234:237], v[114:117]
	ds_read_b128 v[246:249], v233 offset:4096
	s_waitcnt lgkmcnt(5)
	v_mfma_f32_16x16x32_bf16 v[118:121], v[250:253], v[212:215], v[118:121]
	v_mfma_f32_16x16x32_bf16 v[122:125], v[250:253], v[216:219], v[122:125]
	v_mfma_f32_16x16x32_bf16 v[126:129], v[250:253], v[220:223], v[126:129]
	v_mfma_f32_16x16x32_bf16 v[2:5], v[250:253], v[234:237], v[2:5]
	ds_read_b128 v[250:253], v233 offset:6144
	s_waitcnt lgkmcnt(3)
	v_mfma_f32_16x16x32_bf16 v[6:9], v[238:241], v[130:133], v[6:9]
	v_mfma_f32_16x16x32_bf16 v[10:13], v[238:241], v[134:137], v[10:13]
	v_mfma_f32_16x16x32_bf16 v[14:17], v[238:241], v[138:141], v[14:17]
	v_mfma_f32_16x16x32_bf16 v[18:21], v[238:241], v[142:145], v[18:21]
	ds_read_b128 v[238:241], v233 offset:8192
	s_waitcnt lgkmcnt(3)
	v_mfma_f32_16x16x32_bf16 v[22:25], v[242:245], v[130:133], v[22:25]
	v_mfma_f32_16x16x32_bf16 v[26:29], v[242:245], v[134:137], v[26:29]
	v_mfma_f32_16x16x32_bf16 v[30:33], v[242:245], v[138:141], v[30:33]
	v_mfma_f32_16x16x32_bf16 v[34:37], v[242:245], v[142:145], v[34:37]
	ds_read_b128 v[242:245], v233 offset:10240
	s_waitcnt lgkmcnt(3)
	v_mfma_f32_16x16x32_bf16 v[38:41], v[246:249], v[130:133], v[38:41]
	v_mfma_f32_16x16x32_bf16 v[42:45], v[246:249], v[134:137], v[42:45]
	v_mfma_f32_16x16x32_bf16 v[46:49], v[246:249], v[138:141], v[46:49]
	v_mfma_f32_16x16x32_bf16 v[50:53], v[246:249], v[142:145], v[50:53]
	ds_read_b128 v[246:249], v233 offset:12288
	s_waitcnt lgkmcnt(3)
	v_mfma_f32_16x16x32_bf16 v[54:57], v[250:253], v[130:133], v[54:57]
	v_mfma_f32_16x16x32_bf16 v[58:61], v[250:253], v[134:137], v[58:61]
	v_mfma_f32_16x16x32_bf16 v[62:65], v[250:253], v[138:141], v[62:65]
	v_mfma_f32_16x16x32_bf16 v[66:69], v[250:253], v[142:145], v[66:69]
	ds_read_b128 v[250:253], v233 offset:14336
	s_waitcnt lgkmcnt(3)
	v_mfma_f32_16x16x32_bf16 v[70:73], v[238:241], v[130:133], v[70:73]
	v_mfma_f32_16x16x32_bf16 v[74:77], v[238:241], v[134:137], v[74:77]
	v_mfma_f32_16x16x32_bf16 v[78:81], v[238:241], v[138:141], v[78:81]
	v_mfma_f32_16x16x32_bf16 v[82:85], v[238:241], v[142:145], v[82:85]
	s_waitcnt lgkmcnt(2)
	v_mfma_f32_16x16x32_bf16 v[86:89], v[242:245], v[130:133], v[86:89]
	v_mfma_f32_16x16x32_bf16 v[90:93], v[242:245], v[134:137], v[90:93]
	v_mfma_f32_16x16x32_bf16 v[94:97], v[242:245], v[138:141], v[94:97]
	v_mfma_f32_16x16x32_bf16 v[98:101], v[242:245], v[142:145], v[98:101]
	s_waitcnt lgkmcnt(0)
	s_waitcnt vmcnt(0)
	s_barrier
; #define GCOMPUTE(AS, BS) GCOMPUTE_KS(AS, BS, 0) GCOMPUTE_KS(AS, BS, 1)
; template <int EPI>
; DI void gemm_phase(const P& p, int l, const u16* __restrict__ A, const u16* __restrict__ Bt, int mpx, char* lds) {
;     ...
;   GCOMPUTE(As1, Bs1)
;   __builtin_amdgcn_sched_barrier(0);
;     ...
;     const int cb = n0 + wn * 64;
;     const bool isctx = m0 >= MLAT;
;     const int b = isctx ? ((m0 - MLAT) >> 8) : (m0 >> 11);
;     const int tokw = (isctx ? 2048 + ((m0 - MLAT) & 255) : (m0 & 2047)) + wm * 128;
;     u16* Tl = (u16*)(lds + 65536) + w * (64 * 72);
;     int kind = 0;
;     int tr = 0;
;     bool donorm = false;
;     if (cb >= 2816) { kind = 2; tr = 1; }
;     else if (cb < 256) tr = 1;
;     else if (cb < 512) tr = 0;
;     else if (cb < 1024) tr = 2;
;     else if (cb < 1408) { tr = 3; donorm = true; }
;     else if (cb < 1536) kind = 1;
;     else if (cb < 2048) tr = isctx ? 0 : 4;
;     else if (cb < 2304) kind = 1;
;     else if (cb < 2688) tr = isctx ? 0 : 3;
;     else kind = 1;
	v_mfma_f32_16x16x32_bf16 v[102:105], v[246:249], v[130:133], v[102:105]
	v_mfma_f32_16x16x32_bf16 v[106:109], v[246:249], v[134:137], v[106:109]
	v_mfma_f32_16x16x32_bf16 v[110:113], v[246:249], v[138:141], v[110:113]
	v_mfma_f32_16x16x32_bf16 v[114:117], v[246:249], v[142:145], v[114:117]
	v_mfma_f32_16x16x32_bf16 v[118:121], v[250:253], v[130:133], v[118:121]
	v_mfma_f32_16x16x32_bf16 v[122:125], v[250:253], v[134:137], v[122:125]
	v_mfma_f32_16x16x32_bf16 v[126:129], v[250:253], v[138:141], v[126:129]
	v_mfma_f32_16x16x32_bf16 v[2:5], v[250:253], v[142:145], v[2:5]
	s_nop 0
	v_readfirstlane_b32 s40, v195
	s_lshr_b32 s40, s40, 6
	s_and_b32 s41, s40, 3
	s_lshr_b32 s42, s40, 2
	s_lshr_b32 s43, s46, 6
	s_add_i32 s43, s43, s41
	s_cmp_ge_u32 s66, 0x8000
	s_cselect_b32 s67, 1, 0
	s_mov_b32 s44, 0xffff
	s_mov_b32 s45, 0
	s_bitcmp1_b64 s[44:45], s43
	s_cbranch_scc1 .Lfe_kind0
	s_mov_b32 s44, 0xc00000
	s_mov_b32 s45, 0xc0f
	s_bitcmp1_b64 s[44:45], s43
	s_cbranch_scc1 .Lfe_kind1
	s_cmp_ge_u32 s43, 44
	s_cbranch_scc1 .Lfe_kind2
	s_branch .Lfe_kind0
